# route q-GEMM: last K chunk after the loop now uses software-pipelined LDS fragment reads
# baseline (speedup 1.0000x reference)
.LBB0_1004:
	s_and_b32 s77, s76, 1
	s_mul_i32 s78, s77, 0x4800
	v_lshl_add_u64 v[96:97], v[160:161], 0, s[58:59]
	v_lshl_add_u64 v[100:101], v[168:169], 0, s[58:59]
	v_lshl_add_u64 v[104:105], v[162:163], 0, s[58:59]
	v_lshl_add_u64 v[108:109], v[170:171], 0, s[58:59]
	v_lshl_add_u64 v[112:113], v[164:165], 0, s[58:59]
	v_lshl_add_u64 v[116:117], v[172:173], 0, s[58:59]
	v_lshl_add_u64 v[120:121], v[166:167], 0, s[58:59]
	v_lshl_add_u64 v[124:125], v[174:175], 0, s[58:59]
	v_add3_u32 v197, s78, v232, v231
	global_load_dwordx4 v[96:99], v[96:97], off
	s_nop 0
	global_load_dwordx4 v[100:103], v[100:101], off
	s_nop 0
	global_load_dwordx4 v[104:107], v[104:105], off
	s_nop 0
	global_load_dwordx4 v[108:111], v[108:109], off
	s_nop 0
	global_load_dwordx4 v[112:115], v[112:113], off
	s_nop 0
	global_load_dwordx4 v[116:119], v[116:117], off
	s_nop 0
	global_load_dwordx4 v[120:123], v[120:121], off
	s_nop 0
	global_load_dwordx4 v[124:127], v[124:125], off
	v_add3_u32 v198, s78, v234, v231
	ds_read_b128 v[242:245], v198 offset:36864
	ds_read_b128 v[238:241], v197
	ds_read_b128 v[246:249], v197 offset:4608
	ds_read_b128 v[200:203], v197 offset:9216
	ds_read_b128 v[204:207], v197 offset:13824
	s_waitcnt lgkmcnt(3)
	v_mfma_f32_32x32x16_bf16 v[48:63], v[238:241], v[242:245], v[48:63]
	ds_read_b128 v[208:211], v198 offset:36896
	ds_read_b128 v[238:241], v197 offset:32
	s_add_i32 s76, s76, 1
	s_xor_b32 s79, s77, 1
	s_xor_b32 s80, s77, 3
	s_mul_i32 s77, s79, 0x4800
	s_add_u32 s58, s58, 0x80
	s_mul_i32 s78, s80, 0x4800
	s_waitcnt lgkmcnt(4)
	v_mfma_f32_32x32x16_bf16 v[32:47], v[246:249], v[242:245], v[32:47]
	ds_read_b128 v[246:249], v197 offset:4640
	v_or_b32_e32 v250, s77, v128
	s_addc_u32 s59, s59, 0
	v_or_b32_e32 v251, s78, v128
	v_add_u32_e32 v252, v250, v233
	s_cmpk_lg_i32 s58, 0x780
	v_add_u32_e32 v177, v251, v233
	s_waitcnt lgkmcnt(4)
	v_mfma_f32_32x32x16_bf16 v[16:31], v[200:203], v[242:245], v[16:31]
	ds_read_b128 v[200:203], v197 offset:9248
	s_waitcnt lgkmcnt(4)
	v_mfma_f32_32x32x16_bf16 v[0:15], v[204:207], v[242:245], v[0:15]
	ds_read_b128 v[204:207], v197 offset:13856
	s_waitcnt lgkmcnt(3)
	v_mfma_f32_32x32x16_bf16 v[48:63], v[238:241], v[208:211], v[48:63]
	ds_read_b128 v[242:245], v198 offset:36928
	ds_read_b128 v[238:241], v197 offset:64
	s_waitcnt lgkmcnt(4)
	v_mfma_f32_32x32x16_bf16 v[32:47], v[246:249], v[208:211], v[32:47]
	ds_read_b128 v[246:249], v197 offset:4672
	s_waitcnt lgkmcnt(4)
	v_mfma_f32_32x32x16_bf16 v[16:31], v[200:203], v[208:211], v[16:31]
	ds_read_b128 v[200:203], v197 offset:9280
	s_waitcnt lgkmcnt(4)
	v_mfma_f32_32x32x16_bf16 v[0:15], v[204:207], v[208:211], v[0:15]
	ds_read_b128 v[204:207], v197 offset:13888
	s_waitcnt lgkmcnt(3)
	v_mfma_f32_32x32x16_bf16 v[48:63], v[238:241], v[242:245], v[48:63]
	ds_read_b128 v[208:211], v198 offset:36960
	ds_read_b128 v[238:241], v197 offset:96
	s_waitcnt lgkmcnt(4)
	v_mfma_f32_32x32x16_bf16 v[32:47], v[246:249], v[242:245], v[32:47]
	ds_read_b128 v[246:249], v197 offset:4704
	s_waitcnt lgkmcnt(4)
	v_mfma_f32_32x32x16_bf16 v[16:31], v[200:203], v[242:245], v[16:31]
	ds_read_b128 v[200:203], v197 offset:9312
	s_waitcnt lgkmcnt(4)
	v_mfma_f32_32x32x16_bf16 v[0:15], v[204:207], v[242:245], v[0:15]
	ds_read_b128 v[204:207], v197 offset:13920
	s_waitcnt lgkmcnt(3)
	v_mfma_f32_32x32x16_bf16 v[48:63], v[238:241], v[208:211], v[48:63]
	s_waitcnt lgkmcnt(2)
	v_mfma_f32_32x32x16_bf16 v[32:47], v[246:249], v[208:211], v[32:47]
	s_waitcnt lgkmcnt(1)
	v_mfma_f32_32x32x16_bf16 v[16:31], v[200:203], v[208:211], v[16:31]
	v_add_u32_e32 v238, v250, v235
	v_add_u32_e32 v239, v251, v235
	v_add_u32_e32 v240, v250, v236
	v_add_u32_e32 v241, v251, v236
	v_add_u32_e32 v250, v250, v237
	v_add_u32_e32 v251, v251, v237
	s_waitcnt vmcnt(7)
	ds_write_b128 v252, v[96:99]
	s_waitcnt vmcnt(6)
	ds_write_b128 v177, v[100:103]
	s_waitcnt vmcnt(5)
	ds_write_b128 v238, v[104:107]
	s_waitcnt vmcnt(4)
	ds_write_b128 v239, v[108:111]
	s_waitcnt vmcnt(3)
	ds_write_b128 v240, v[112:115]
	s_waitcnt vmcnt(2)
	ds_write_b128 v241, v[116:119]
	s_waitcnt vmcnt(1)
	ds_write_b128 v250, v[120:123]
	s_waitcnt vmcnt(0)
	ds_write_b128 v251, v[124:127]
	s_waitcnt lgkmcnt(8)
	v_mfma_f32_32x32x16_bf16 v[0:15], v[204:207], v[208:211], v[0:15]
	s_waitcnt lgkmcnt(0)
	s_barrier
	s_cbranch_scc1 .LBB0_1004
	v_or_b32_e32 v197, 0x61, v193
	v_or_b32_e32 v198, 0x62, v193
	v_or_b32_e32 v199, 0x63, v193
	v_or_b32_e32 v200, 0x68, v193
	v_or_b32_e32 v201, 0x69, v193
	v_or_b32_e32 v202, 0x6a, v193
	v_or_b32_e32 v203, 0x6b, v193
	v_or_b32_e32 v204, 0x70, v193
	v_or_b32_e32 v205, 0x71, v193
	v_or_b32_e32 v206, 0x72, v193
	v_or_b32_e32 v207, 0x73, v193
	v_or_b32_e32 v208, 0x78, v193
	v_or_b32_e32 v209, 0x79, v193
	v_or_b32_e32 v210, 0x7a, v193
	v_or_b32_e32 v211, 0x7b, v193
	v_add_u32_e32 v250, v232, v231
	v_add_u32_e32 v251, v234, v231
	s_mov_b32 s80, 1
	s_mov_b64 s[58:59], 0
	ds_read_b128 v[238:241], v251 offset:55296
	ds_read_b128 v[112:115], v250 offset:18432
	ds_read_b128 v[116:119], v250 offset:23040
	ds_read_b128 v[120:123], v250 offset:27648
	ds_read_b128 v[124:127], v250 offset:32256
	s_waitcnt lgkmcnt(3)
	v_mfma_f32_32x32x16_bf16 v[48:63], v[112:115], v[238:241], v[48:63]
	ds_read_b128 v[100:103], v251 offset:55328
	ds_read_b128 v[112:115], v250 offset:18464
	s_waitcnt lgkmcnt(4)
	v_mfma_f32_32x32x16_bf16 v[32:47], v[116:119], v[238:241], v[32:47]
	ds_read_b128 v[116:119], v250 offset:23072
	s_waitcnt lgkmcnt(4)
	v_mfma_f32_32x32x16_bf16 v[16:31], v[120:123], v[238:241], v[16:31]
	ds_read_b128 v[120:123], v250 offset:27680
	s_waitcnt lgkmcnt(4)
	v_mfma_f32_32x32x16_bf16 v[0:15], v[124:127], v[238:241], v[0:15]
	ds_read_b128 v[124:127], v250 offset:32288
	s_waitcnt lgkmcnt(3)
	v_mfma_f32_32x32x16_bf16 v[48:63], v[112:115], v[100:103], v[48:63]
	ds_read_b128 v[238:241], v251 offset:55360
	ds_read_b128 v[112:115], v250 offset:18496
	s_waitcnt lgkmcnt(4)
	v_mfma_f32_32x32x16_bf16 v[32:47], v[116:119], v[100:103], v[32:47]
	ds_read_b128 v[116:119], v250 offset:23104
	s_waitcnt lgkmcnt(4)
	v_mfma_f32_32x32x16_bf16 v[16:31], v[120:123], v[100:103], v[16:31]
	ds_read_b128 v[120:123], v250 offset:27712
	s_waitcnt lgkmcnt(4)
	v_mfma_f32_32x32x16_bf16 v[0:15], v[124:127], v[100:103], v[0:15]
	ds_read_b128 v[124:127], v250 offset:32320
	s_waitcnt lgkmcnt(3)
	v_mfma_f32_32x32x16_bf16 v[48:63], v[112:115], v[238:241], v[48:63]
	ds_read_b128 v[100:103], v251 offset:55392
	ds_read_b128 v[112:115], v250 offset:18528
	s_waitcnt lgkmcnt(4)
	v_mfma_f32_32x32x16_bf16 v[32:47], v[116:119], v[238:241], v[32:47]
	ds_read_b128 v[96:99], v250 offset:23136
	s_waitcnt lgkmcnt(4)
	v_mfma_f32_32x32x16_bf16 v[16:31], v[120:123], v[238:241], v[16:31]
	ds_read_b128 v[104:107], v250 offset:27744
	s_waitcnt lgkmcnt(4)
	v_mfma_f32_32x32x16_bf16 v[0:15], v[124:127], v[238:241], v[0:15]
	ds_read_b128 v[108:111], v250 offset:32352
	s_waitcnt lgkmcnt(3)
	v_mfma_f32_32x32x16_bf16 v[48:63], v[112:115], v[100:103], v[48:63]
	s_waitcnt lgkmcnt(0)
	s_barrier
	ds_write_b128 v212, v[64:67]
	ds_write_b128 v213, v[68:71]
	ds_write_b128 v214, v[72:75]
	ds_write_b128 v215, v[76:79]
	ds_write_b128 v216, v[80:83]
	ds_write_b128 v217, v[84:87]
	ds_write_b128 v218, v[88:91]
	ds_write_b128 v219, v[92:95]
	s_waitcnt lgkmcnt(0)
	s_barrier
	ds_read2_b64 v[64:67], v196 offset1:2
	v_cvt_pk_bf16_f32 v80, v48, v49
	v_cvt_pk_bf16_f32 v81, v50, v51
	v_cvt_pk_bf16_f32 v82, v52, v53
	v_cvt_pk_bf16_f32 v83, v54, v55
	ds_read2_b64 v[48:51], v196 offset0:4 offset1:6
	v_cvt_pk_bf16_f32 v56, v56, v57
	s_waitcnt lgkmcnt(1)
	v_mfma_f32_32x32x16_bf16 v[64:79], v[64:67], v[80:83], 0
	v_cvt_pk_bf16_f32 v57, v58, v59
	v_cvt_pk_bf16_f32 v58, v60, v61
	v_cvt_pk_bf16_f32 v59, v62, v63
	v_add_u32_e32 v94, 0x4000, v196
	ds_read2_b64 v[90:93], v94 offset0:132 offset1:134
	v_mfma_f32_32x32x16_bf16 v[32:47], v[96:99], v[100:103], v[32:47]
	s_waitcnt lgkmcnt(1)
	v_mfma_f32_32x32x16_bf16 v[64:79], v[48:51], v[56:59], v[64:79]
	ds_read2_b64 v[48:51], v196 offset0:8 offset1:10
	s_nop 8
	v_cvt_pk_bf16_f32 v52, v32, v33
	v_cvt_pk_bf16_f32 v53, v34, v35
	v_cvt_pk_bf16_f32 v54, v36, v37
	v_cvt_pk_bf16_f32 v55, v38, v39
	ds_read2_b64 v[32:35], v196 offset0:12 offset1:14
	s_waitcnt lgkmcnt(1)
	v_mfma_f32_32x32x16_bf16 v[64:79], v[48:51], v[52:55], v[64:79]
	v_cvt_pk_bf16_f32 v48, v40, v41
	v_cvt_pk_bf16_f32 v49, v42, v43
	v_cvt_pk_bf16_f32 v50, v44, v45
	v_cvt_pk_bf16_f32 v51, v46, v47
	v_mfma_f32_32x32x16_bf16 v[16:31], v[104:107], v[100:103], v[16:31]
	s_waitcnt lgkmcnt(0)
	v_mfma_f32_32x32x16_bf16 v[64:79], v[32:35], v[48:51], v[64:79]
	ds_read2_b64 v[32:35], v196 offset0:16 offset1:18
	s_nop 8
	v_cvt_pk_bf16_f32 v44, v16, v17
	v_cvt_pk_bf16_f32 v45, v18, v19
	v_cvt_pk_bf16_f32 v46, v20, v21
	v_cvt_pk_bf16_f32 v47, v22, v23
	ds_read2_b64 v[16:19], v196 offset0:20 offset1:22
	v_cvt_pk_bf16_f32 v40, v24, v25
	s_waitcnt lgkmcnt(1)
	v_mfma_f32_32x32x16_bf16 v[64:79], v[32:35], v[44:47], v[64:79]
	v_cvt_pk_bf16_f32 v41, v26, v27
	v_cvt_pk_bf16_f32 v42, v28, v29
	v_cvt_pk_bf16_f32 v43, v30, v31
	v_add_u32_e32 v24, 0x2000, v196
	v_or_b32_e32 v22, 9, v193
	v_mfma_f32_32x32x16_bf16 v[0:15], v[108:111], v[100:103], v[0:15]
	v_add_u32_e32 v100, 0x6000, v196
	s_waitcnt lgkmcnt(0)
	v_mfma_f32_32x32x16_bf16 v[64:79], v[16:19], v[40:43], v[64:79]
	ds_read2_b64 v[16:19], v196 offset0:24 offset1:26
	s_nop 7
	v_cvt_pk_bf16_f32 v36, v0, v1
	v_cvt_pk_bf16_f32 v37, v2, v3
	v_cvt_pk_bf16_f32 v38, v4, v5
	v_cvt_pk_bf16_f32 v39, v6, v7
	ds_read2_b64 v[0:3], v196 offset0:28 offset1:30
	v_cvt_pk_bf16_f32 v32, v8, v9
	s_waitcnt lgkmcnt(1)
	v_mfma_f32_32x32x16_bf16 v[64:79], v[16:19], v[36:39], v[64:79]
	v_cvt_pk_bf16_f32 v33, v10, v11
	v_cvt_pk_bf16_f32 v34, v12, v13
	v_cvt_pk_bf16_f32 v35, v14, v15
	v_or_b32_e32 v6, 3, v193
	ds_read2_b64 v[16:19], v24 offset0:68 offset1:70
	s_waitcnt lgkmcnt(1)
	v_mfma_f32_32x32x16_bf16 v[64:79], v[0:3], v[32:35], v[64:79]
	v_or_b32_e32 v2, 1, v193
	s_nop 10
	v_ashrrev_i32_e32 v1, 31, v64
	v_and_b32_e32 v0, 0xffffff80, v64
	v_and_b32_e32 v1, 0x7fffffff, v1
	v_bitop3_b32 v60, v0, v1, v193 bitop3:0x36
	v_ashrrev_i32_e32 v1, 31, v65
	v_and_b32_e32 v0, 0xffffff80, v65
	v_and_b32_e32 v1, 0x7fffffff, v1
	v_bitop3_b32 v61, v0, v1, v2 bitop3:0x36
	v_ashrrev_i32_e32 v1, 31, v66
	v_and_b32_e32 v0, 0xffffff80, v66
	v_and_b32_e32 v1, 0x7fffffff, v1
	v_or_b32_e32 v2, 2, v193
	v_bitop3_b32 v62, v0, v1, v2 bitop3:0x36
	ds_read2_b64 v[0:3], v24 offset0:64 offset1:66
	v_ashrrev_i32_e32 v5, 31, v67
	v_and_b32_e32 v4, 0xffffff80, v67
	v_and_b32_e32 v5, 0x7fffffff, v5
	v_bitop3_b32 v63, v4, v5, v6 bitop3:0x36
	v_ashrrev_i32_e32 v5, 31, v68
	v_and_b32_e32 v4, 0xffffff80, v68
	v_and_b32_e32 v5, 0x7fffffff, v5
	v_or_b32_e32 v6, 8, v193
	v_bitop3_b32 v64, v4, v5, v6 bitop3:0x36
	s_waitcnt lgkmcnt(0)
	v_mfma_f32_32x32x16_bf16 v[0:15], v[0:3], v[80:83], 0
	v_ashrrev_i32_e32 v21, 31, v69
	v_and_b32_e32 v20, 0xffffff80, v69
	v_and_b32_e32 v21, 0x7fffffff, v21
	v_bitop3_b32 v68, v20, v21, v22 bitop3:0x36
	v_ashrrev_i32_e32 v20, 31, v70
	v_and_b32_e32 v26, 0x7fffffff, v20
	ds_read2_b64 v[20:23], v24 offset0:72 offset1:74
	v_mfma_f32_32x32x16_bf16 v[0:15], v[16:19], v[56:59], v[0:15]
	v_and_b32_e32 v25, 0xffffff80, v70
	v_or_b32_e32 v16, 10, v193
	v_ashrrev_i32_e32 v17, 31, v71
	v_bitop3_b32 v69, v25, v26, v16 bitop3:0x36
	v_and_b32_e32 v16, 0xffffff80, v71
	v_and_b32_e32 v17, 0x7fffffff, v17
	v_or_b32_e32 v18, 11, v193
	v_bitop3_b32 v70, v16, v17, v18 bitop3:0x36
	ds_read2_b64 v[16:19], v24 offset0:76 offset1:78
	s_waitcnt lgkmcnt(1)
	v_mfma_f32_32x32x16_bf16 v[0:15], v[20:23], v[52:55], v[0:15]
	v_ashrrev_i32_e32 v20, 31, v72
	v_and_b32_e32 v25, 0xffffff80, v72
	v_and_b32_e32 v20, 0x7fffffff, v20
	v_or_b32_e32 v21, 16, v193
	v_bitop3_b32 v71, v25, v20, v21 bitop3:0x36
	v_ashrrev_i32_e32 v20, 31, v73
	v_and_b32_e32 v26, 0x7fffffff, v20
	ds_read2_b64 v[20:23], v24 offset0:80 offset1:82
	s_waitcnt lgkmcnt(1)
	v_mfma_f32_32x32x16_bf16 v[0:15], v[16:19], v[48:51], v[0:15]
	v_and_b32_e32 v25, 0xffffff80, v73
	v_or_b32_e32 v16, 17, v193
	v_ashrrev_i32_e32 v17, 31, v74
	v_bitop3_b32 v72, v25, v26, v16 bitop3:0x36
	v_and_b32_e32 v16, 0xffffff80, v74
	v_and_b32_e32 v17, 0x7fffffff, v17
	v_or_b32_e32 v18, 18, v193
	v_bitop3_b32 v74, v16, v17, v18 bitop3:0x36
	ds_read2_b64 v[16:19], v24 offset0:84 offset1:86
	s_waitcnt lgkmcnt(1)
	v_mfma_f32_32x32x16_bf16 v[0:15], v[20:23], v[44:47], v[0:15]
	v_ashrrev_i32_e32 v20, 31, v75
	v_and_b32_e32 v25, 0xffffff80, v75
	v_and_b32_e32 v20, 0x7fffffff, v20
	v_or_b32_e32 v21, 19, v193
	v_bitop3_b32 v84, v25, v20, v21 bitop3:0x36
	v_ashrrev_i32_e32 v20, 31, v76
	v_and_b32_e32 v26, 0x7fffffff, v20
	ds_read2_b64 v[20:23], v24 offset0:88 offset1:90
	s_waitcnt lgkmcnt(1)
	v_mfma_f32_32x32x16_bf16 v[0:15], v[16:19], v[40:43], v[0:15]
	v_and_b32_e32 v25, 0xffffff80, v76
	v_or_b32_e32 v16, 24, v193
	v_ashrrev_i32_e32 v17, 31, v77
	v_bitop3_b32 v85, v25, v26, v16 bitop3:0x36
	v_and_b32_e32 v16, 0xffffff80, v77
	v_and_b32_e32 v17, 0x7fffffff, v17
	v_or_b32_e32 v18, 25, v193
	v_bitop3_b32 v86, v16, v17, v18 bitop3:0x36
	ds_read2_b64 v[16:19], v24 offset0:92 offset1:94
	s_waitcnt lgkmcnt(1)
	v_mfma_f32_32x32x16_bf16 v[0:15], v[20:23], v[36:39], v[0:15]
	v_ashrrev_i32_e32 v20, 31, v78
	v_and_b32_e32 v25, 0xffffff80, v78
	v_and_b32_e32 v20, 0x7fffffff, v20
	v_or_b32_e32 v21, 26, v193
	v_bitop3_b32 v87, v25, v20, v21 bitop3:0x36
	v_ashrrev_i32_e32 v21, 31, v79
	v_and_b32_e32 v20, 0xffffff80, v79
	s_waitcnt lgkmcnt(0)
	v_mfma_f32_32x32x16_bf16 v[0:15], v[16:19], v[32:35], v[0:15]
	v_or_b32_e32 v17, 32, v193
	v_or_b32_e32 v18, 35, v193
	v_and_b32_e32 v21, 0x7fffffff, v21
	v_or_b32_e32 v22, 27, v193
	v_bitop3_b32 v88, v20, v21, v22 bitop3:0x36
	s_nop 6
	v_and_b32_e32 v16, 0xffffff80, v0
	v_ashrrev_i32_e32 v0, 31, v0
	v_and_b32_e32 v0, 0x7fffffff, v0
	v_bitop3_b32 v65, v16, v0, v17 bitop3:0x36
	v_and_b32_e32 v0, 0xffffff80, v1
	v_ashrrev_i32_e32 v1, 31, v1
	v_and_b32_e32 v1, 0x7fffffff, v1
	v_or_b32_e32 v16, 33, v193
	v_bitop3_b32 v66, v0, v1, v16 bitop3:0x36
	v_ashrrev_i32_e32 v1, 31, v2
	v_and_b32_e32 v0, 0xffffff80, v2
	v_and_b32_e32 v1, 0x7fffffff, v1
	v_or_b32_e32 v2, 34, v193
	v_bitop3_b32 v67, v0, v1, v2 bitop3:0x36
	v_and_b32_e32 v16, 0xffffff80, v3
	v_ashrrev_i32_e32 v17, 31, v3
	ds_read2_b64 v[0:3], v94 offset0:128 offset1:130
	v_and_b32_e32 v17, 0x7fffffff, v17
	v_bitop3_b32 v73, v16, v17, v18 bitop3:0x36
	v_and_b32_e32 v16, 0xffffff80, v4
	v_ashrrev_i32_e32 v4, 31, v4
	v_and_b32_e32 v4, 0x7fffffff, v4
	v_or_b32_e32 v17, 40, v193
	v_bitop3_b32 v75, v16, v4, v17 bitop3:0x36
	s_waitcnt lgkmcnt(0)
	v_mfma_f32_32x32x16_bf16 v[16:31], v[0:3], v[80:83], 0
	v_ashrrev_i32_e32 v0, 31, v5
	v_and_b32_e32 v4, 0xffffff80, v5
	v_and_b32_e32 v0, 0x7fffffff, v0
	v_or_b32_e32 v1, 41, v193
	v_bitop3_b32 v76, v4, v0, v1 bitop3:0x36
	v_ashrrev_i32_e32 v0, 31, v6
	v_and_b32_e32 v5, 0x7fffffff, v0
	ds_read2_b64 v[0:3], v94 offset0:136 offset1:138
	v_mfma_f32_32x32x16_bf16 v[16:31], v[90:93], v[56:59], v[16:31]
	v_and_b32_e32 v4, 0xffffff80, v6
	v_or_b32_e32 v6, 42, v193
	v_bitop3_b32 v77, v4, v5, v6 bitop3:0x36
	v_ashrrev_i32_e32 v5, 31, v7
	v_and_b32_e32 v4, 0xffffff80, v7
	v_and_b32_e32 v5, 0x7fffffff, v5
	v_or_b32_e32 v6, 43, v193
	v_bitop3_b32 v78, v4, v5, v6 bitop3:0x36
	ds_read2_b64 v[4:7], v94 offset0:140 offset1:142
	s_waitcnt lgkmcnt(1)
	v_mfma_f32_32x32x16_bf16 v[16:31], v[0:3], v[52:55], v[16:31]
	v_ashrrev_i32_e32 v0, 31, v8
	v_and_b32_e32 v79, 0xffffff80, v8
	v_and_b32_e32 v0, 0x7fffffff, v0
	v_or_b32_e32 v1, 48, v193
	v_bitop3_b32 v79, v79, v0, v1 bitop3:0x36
	v_ashrrev_i32_e32 v0, 31, v9
	v_and_b32_e32 v8, 0xffffff80, v9
	v_and_b32_e32 v9, 0x7fffffff, v0
	ds_read2_b64 v[0:3], v94 offset0:144 offset1:146
	s_waitcnt lgkmcnt(1)
	v_mfma_f32_32x32x16_bf16 v[16:31], v[4:7], v[48:51], v[16:31]
	v_or_b32_e32 v4, 49, v193
	v_ashrrev_i32_e32 v5, 31, v10
	v_bitop3_b32 v89, v8, v9, v4 bitop3:0x36
	v_and_b32_e32 v4, 0xffffff80, v10
	v_and_b32_e32 v5, 0x7fffffff, v5
	v_or_b32_e32 v6, 50, v193
	v_bitop3_b32 v90, v4, v5, v6 bitop3:0x36
	ds_read2_b64 v[4:7], v94 offset0:148 offset1:150
	s_waitcnt lgkmcnt(1)
	v_mfma_f32_32x32x16_bf16 v[16:31], v[0:3], v[44:47], v[16:31]
	v_ashrrev_i32_e32 v0, 31, v11
	v_and_b32_e32 v8, 0xffffff80, v11
	v_and_b32_e32 v0, 0x7fffffff, v0
	v_or_b32_e32 v1, 51, v193
	v_bitop3_b32 v91, v8, v0, v1 bitop3:0x36
	v_ashrrev_i32_e32 v0, 31, v12
	v_and_b32_e32 v9, 0x7fffffff, v0
	ds_read2_b64 v[0:3], v94 offset0:152 offset1:154
	s_waitcnt lgkmcnt(1)
	v_mfma_f32_32x32x16_bf16 v[16:31], v[4:7], v[40:43], v[16:31]
	v_and_b32_e32 v8, 0xffffff80, v12
	v_or_b32_e32 v4, 56, v193
	v_ashrrev_i32_e32 v5, 31, v13
	v_bitop3_b32 v96, v8, v9, v4 bitop3:0x36
	v_and_b32_e32 v4, 0xffffff80, v13
	v_and_b32_e32 v5, 0x7fffffff, v5
	v_or_b32_e32 v6, 57, v193
	v_bitop3_b32 v97, v4, v5, v6 bitop3:0x36
	ds_read2_b64 v[4:7], v94 offset0:156 offset1:158
	s_waitcnt lgkmcnt(1)
	v_mfma_f32_32x32x16_bf16 v[16:31], v[0:3], v[36:39], v[16:31]
	v_ashrrev_i32_e32 v0, 31, v14
	v_and_b32_e32 v8, 0xffffff80, v14
	v_and_b32_e32 v0, 0x7fffffff, v0
	v_or_b32_e32 v1, 58, v193
	v_bitop3_b32 v98, v8, v0, v1 bitop3:0x36
	v_ashrrev_i32_e32 v1, 31, v15
	v_and_b32_e32 v0, 0xffffff80, v15
	s_waitcnt lgkmcnt(0)
	v_mfma_f32_32x32x16_bf16 v[16:31], v[4:7], v[32:35], v[16:31]
	v_and_b32_e32 v1, 0x7fffffff, v1
	v_or_b32_e32 v2, 59, v193
	v_bitop3_b32 v99, v0, v1, v2 bitop3:0x36
	v_or_b32_e32 v2, 64, v193
	v_or_b32_e32 v6, 0x43, v193
	ds_read2_b64 v[92:95], v100 offset0:196 offset1:198
	s_nop 5
	v_ashrrev_i32_e32 v1, 31, v16
	v_and_b32_e32 v0, 0xffffff80, v16
	v_and_b32_e32 v1, 0x7fffffff, v1
	v_bitop3_b32 v16, v0, v1, v2 bitop3:0x36
	v_ashrrev_i32_e32 v1, 31, v17
	v_and_b32_e32 v0, 0xffffff80, v17
	v_and_b32_e32 v1, 0x7fffffff, v1
	v_or_b32_e32 v2, 0x41, v193
	v_bitop3_b32 v17, v0, v1, v2 bitop3:0x36
	v_ashrrev_i32_e32 v1, 31, v18
	v_and_b32_e32 v0, 0xffffff80, v18
	v_and_b32_e32 v1, 0x7fffffff, v1
	v_or_b32_e32 v2, 0x42, v193
	v_bitop3_b32 v18, v0, v1, v2 bitop3:0x36
	ds_read2_b64 v[0:3], v100 offset0:192 offset1:194
	v_ashrrev_i32_e32 v5, 31, v19
	v_and_b32_e32 v4, 0xffffff80, v19
	v_and_b32_e32 v5, 0x7fffffff, v5
	v_bitop3_b32 v19, v4, v5, v6 bitop3:0x36
	v_ashrrev_i32_e32 v5, 31, v20
	v_and_b32_e32 v4, 0xffffff80, v20
	v_and_b32_e32 v5, 0x7fffffff, v5
	v_or_b32_e32 v6, 0x48, v193
	v_bitop3_b32 v20, v4, v5, v6 bitop3:0x36
	s_waitcnt lgkmcnt(0)
	v_mfma_f32_32x32x16_bf16 v[0:15], v[0:3], v[80:83], 0
	v_and_b32_e32 v101, 0xffffff80, v21
	v_ashrrev_i32_e32 v21, 31, v21
	v_and_b32_e32 v21, 0x7fffffff, v21
	v_or_b32_e32 v80, 0x49, v193
	v_bitop3_b32 v21, v101, v21, v80 bitop3:0x36
	ds_read2_b64 v[80:83], v100 offset0:200 offset1:202
	v_and_b32_e32 v101, 0xffffff80, v22
	v_mfma_f32_32x32x16_bf16 v[0:15], v[92:95], v[56:59], v[0:15]
	v_ashrrev_i32_e32 v22, 31, v22
	v_and_b32_e32 v22, 0x7fffffff, v22
	v_or_b32_e32 v56, 0x4a, v193
	v_bitop3_b32 v92, v101, v22, v56 bitop3:0x36
	v_and_b32_e32 v22, 0xffffff80, v23
	v_ashrrev_i32_e32 v23, 31, v23
	v_and_b32_e32 v23, 0x7fffffff, v23
	v_or_b32_e32 v56, 0x4b, v193
	v_bitop3_b32 v93, v22, v23, v56 bitop3:0x36
	ds_read2_b64 v[56:59], v100 offset0:204 offset1:206
	s_waitcnt lgkmcnt(1)
	v_mfma_f32_32x32x16_bf16 v[0:15], v[80:83], v[52:55], v[0:15]
	v_ashrrev_i32_e32 v23, 31, v24
	v_and_b32_e32 v22, 0xffffff80, v24
	v_and_b32_e32 v23, 0x7fffffff, v23
	v_or_b32_e32 v24, 0x50, v193
	v_bitop3_b32 v52, v22, v23, v24 bitop3:0x36
	v_ashrrev_i32_e32 v22, 31, v25
	v_and_b32_e32 v53, 0xffffff80, v25
	v_and_b32_e32 v54, 0x7fffffff, v22
	ds_read2_b64 v[22:25], v100 offset0:208 offset1:210
	s_waitcnt lgkmcnt(1)
	v_mfma_f32_32x32x16_bf16 v[0:15], v[56:59], v[48:51], v[0:15]
	v_or_b32_e32 v48, 0x51, v193
	v_bitop3_b32 v53, v53, v54, v48 bitop3:0x36
	v_and_b32_e32 v48, 0xffffff80, v26
	v_ashrrev_i32_e32 v26, 31, v26
	v_and_b32_e32 v26, 0x7fffffff, v26
	v_or_b32_e32 v49, 0x52, v193
	v_bitop3_b32 v54, v48, v26, v49 bitop3:0x36
	ds_read2_b64 v[48:51], v100 offset0:212 offset1:214
	s_waitcnt lgkmcnt(1)
	v_mfma_f32_32x32x16_bf16 v[0:15], v[22:25], v[44:47], v[0:15]
	v_ashrrev_i32_e32 v22, 31, v27
	v_and_b32_e32 v26, 0xffffff80, v27
	v_and_b32_e32 v22, 0x7fffffff, v22
	v_or_b32_e32 v23, 0x53, v193
	v_bitop3_b32 v44, v26, v22, v23 bitop3:0x36
	v_ashrrev_i32_e32 v22, 31, v28
	v_and_b32_e32 v27, 0x7fffffff, v22
	ds_read2_b64 v[22:25], v100 offset0:216 offset1:218
	s_waitcnt lgkmcnt(1)
	v_mfma_f32_32x32x16_bf16 v[0:15], v[48:51], v[40:43], v[0:15]
	v_and_b32_e32 v26, 0xffffff80, v28
	v_or_b32_e32 v28, 0x58, v193
	v_bitop3_b32 v40, v26, v27, v28 bitop3:0x36
	v_ashrrev_i32_e32 v27, 31, v29
	v_and_b32_e32 v26, 0xffffff80, v29
	v_and_b32_e32 v27, 0x7fffffff, v27
	v_or_b32_e32 v28, 0x59, v193
	v_bitop3_b32 v41, v26, v27, v28 bitop3:0x36
	ds_read2_b64 v[26:29], v100 offset0:220 offset1:222
	s_waitcnt lgkmcnt(1)
	v_mfma_f32_32x32x16_bf16 v[0:15], v[22:25], v[36:39], v[0:15]
	v_ashrrev_i32_e32 v22, 31, v30
	v_and_b32_e32 v42, 0xffffff80, v30
	v_and_b32_e32 v22, 0x7fffffff, v22
	v_or_b32_e32 v23, 0x5a, v193
	v_ashrrev_i32_e32 v24, 31, v31
	v_bitop3_b32 v22, v42, v22, v23 bitop3:0x36
	v_and_b32_e32 v23, 0xffffff80, v31
	s_waitcnt lgkmcnt(0)
	v_mfma_f32_32x32x16_bf16 v[0:15], v[26:29], v[32:35], v[0:15]
	v_and_b32_e32 v24, 0x7fffffff, v24
	v_or_b32_e32 v25, 0x5b, v193
	v_bitop3_b32 v23, v23, v24, v25 bitop3:0x36
	v_or_b32_e32 v25, 0x60, v193
	v_max_i32_e32 v26, v63, v62
	v_min_i32_e32 v27, v63, v62
	v_max_i32_e32 v28, v64, v68
	s_nop 4
	v_and_b32_e32 v24, 0xffffff80, v0
	v_ashrrev_i32_e32 v0, 31, v0
	v_and_b32_e32 v0, 0x7fffffff, v0
	v_bitop3_b32 v0, v24, v0, v25 bitop3:0x36
	v_and_b32_e32 v24, 0xffffff80, v1
	v_ashrrev_i32_e32 v1, 31, v1
	v_and_b32_e32 v1, 0x7fffffff, v1
	v_bitop3_b32 v1, v24, v1, v197 bitop3:0x36
	v_and_b32_e32 v24, 0xffffff80, v2
	v_ashrrev_i32_e32 v2, 31, v2
	v_and_b32_e32 v2, 0x7fffffff, v2
	v_bitop3_b32 v2, v24, v2, v198 bitop3:0x36
	v_and_b32_e32 v24, 0xffffff80, v3
	v_ashrrev_i32_e32 v3, 31, v3
	v_and_b32_e32 v3, 0x7fffffff, v3
	v_bitop3_b32 v3, v24, v3, v199 bitop3:0x36
	v_and_b32_e32 v24, 0xffffff80, v4
	v_ashrrev_i32_e32 v4, 31, v4
	v_and_b32_e32 v4, 0x7fffffff, v4
	v_bitop3_b32 v4, v24, v4, v200 bitop3:0x36
	v_and_b32_e32 v24, 0xffffff80, v5
	v_ashrrev_i32_e32 v5, 31, v5
	v_and_b32_e32 v5, 0x7fffffff, v5
	v_bitop3_b32 v5, v24, v5, v201 bitop3:0x36
	v_and_b32_e32 v24, 0xffffff80, v6
	v_ashrrev_i32_e32 v6, 31, v6
	v_and_b32_e32 v6, 0x7fffffff, v6
	v_bitop3_b32 v6, v24, v6, v202 bitop3:0x36
	v_and_b32_e32 v24, 0xffffff80, v7
	v_ashrrev_i32_e32 v7, 31, v7
	v_and_b32_e32 v7, 0x7fffffff, v7
	v_bitop3_b32 v7, v24, v7, v203 bitop3:0x36
	v_and_b32_e32 v24, 0xffffff80, v8
	v_ashrrev_i32_e32 v8, 31, v8
	v_and_b32_e32 v8, 0x7fffffff, v8
	v_bitop3_b32 v8, v24, v8, v204 bitop3:0x36
	v_and_b32_e32 v24, 0xffffff80, v9
	v_ashrrev_i32_e32 v9, 31, v9
	v_and_b32_e32 v9, 0x7fffffff, v9
	v_bitop3_b32 v9, v24, v9, v205 bitop3:0x36
	v_and_b32_e32 v24, 0xffffff80, v10
	v_ashrrev_i32_e32 v10, 31, v10
	v_and_b32_e32 v10, 0x7fffffff, v10
	v_bitop3_b32 v10, v24, v10, v206 bitop3:0x36
	v_and_b32_e32 v24, 0xffffff80, v11
	v_ashrrev_i32_e32 v11, 31, v11
	v_and_b32_e32 v11, 0x7fffffff, v11
	v_bitop3_b32 v11, v24, v11, v207 bitop3:0x36
	v_and_b32_e32 v24, 0xffffff80, v12
	v_ashrrev_i32_e32 v12, 31, v12
	v_and_b32_e32 v12, 0x7fffffff, v12
	v_bitop3_b32 v12, v24, v12, v208 bitop3:0x36
	v_and_b32_e32 v24, 0xffffff80, v13
	v_ashrrev_i32_e32 v13, 31, v13
	v_and_b32_e32 v13, 0x7fffffff, v13
	v_bitop3_b32 v13, v24, v13, v209 bitop3:0x36
	v_and_b32_e32 v24, 0xffffff80, v14
	v_ashrrev_i32_e32 v14, 31, v14
	v_and_b32_e32 v14, 0x7fffffff, v14
	v_bitop3_b32 v14, v24, v14, v210 bitop3:0x36
	v_and_b32_e32 v24, 0xffffff80, v15
	v_ashrrev_i32_e32 v15, 31, v15
	v_and_b32_e32 v15, 0x7fffffff, v15
	v_bitop3_b32 v15, v24, v15, v211 bitop3:0x36
	v_max_i32_e32 v24, v60, v61
	v_min_i32_e32 v25, v60, v61
	v_min_i32_e32 v29, v64, v68
	v_max_i32_e32 v30, v70, v69
	v_min_i32_e32 v31, v70, v69
	v_max_i32_e32 v32, v71, v72
	v_min_i32_e32 v33, v71, v72
	v_max_i32_e32 v34, v84, v74
	v_min_i32_e32 v35, v84, v74
	v_max_i32_e32 v36, v85, v86
	v_min_i32_e32 v37, v85, v86
	v_max_i32_e32 v38, v88, v87
	v_min_i32_e32 v39, v88, v87
	v_max_i32_e32 v51, v65, v66
	v_min_i32_e32 v55, v65, v66
	v_max_i32_e32 v56, v73, v67
	v_min_i32_e32 v57, v73, v67
	v_max_i32_e32 v58, v75, v76
	v_min_i32_e32 v59, v75, v76
	v_max_i32_e32 v60, v78, v77
	v_min_i32_e32 v61, v78, v77
	v_max_i32_e32 v62, v79, v89
	v_min_i32_e32 v63, v79, v89
	v_max_i32_e32 v64, v91, v90
	v_min_i32_e32 v65, v91, v90
	v_max_i32_e32 v66, v96, v97
	v_min_i32_e32 v67, v96, v97
	v_max_i32_e32 v68, v99, v98
	v_min_i32_e32 v69, v99, v98
	v_max_i32_e32 v78, v16, v17
	v_min_i32_e32 v16, v16, v17
	v_max_i32_e32 v17, v19, v18
	v_min_i32_e32 v18, v19, v18
	v_max_i32_e32 v19, v20, v21
	v_min_i32_e32 v20, v20, v21
	v_max_i32_e32 v21, v93, v92
	v_min_i32_e32 v79, v93, v92
	v_max_i32_e32 v80, v52, v53
	v_min_i32_e32 v52, v52, v53
	v_max_i32_e32 v53, v44, v54
	v_min_i32_e32 v44, v44, v54
	v_max_i32_e32 v54, v40, v41
	v_min_i32_e32 v40, v40, v41
	v_max_i32_e32 v41, v23, v22
	v_min_i32_e32 v22, v23, v22
	v_max_i32_e32 v88, v0, v1
	v_min_i32_e32 v0, v0, v1
	v_max_i32_e32 v1, v3, v2
	v_min_i32_e32 v2, v3, v2
	v_max_i32_e32 v3, v4, v5
	v_min_i32_e32 v4, v4, v5
	v_max_i32_e32 v5, v7, v6
	v_min_i32_e32 v6, v7, v6
	v_max_i32_e32 v7, v8, v9
	v_min_i32_e32 v8, v8, v9
	v_max_i32_e32 v9, v11, v10
	v_min_i32_e32 v10, v11, v10
	v_max_i32_e32 v11, v12, v13
	v_min_i32_e32 v12, v12, v13
	v_max_i32_e32 v13, v15, v14
	v_min_i32_e32 v14, v15, v14
	v_max_i32_e32 v42, v24, v27
	v_min_i32_e32 v24, v24, v27
	v_max_i32_e32 v27, v25, v26
	v_min_i32_e32 v25, v25, v26
	v_max_i32_e32 v26, v31, v28
	v_min_i32_e32 v28, v31, v28
	v_max_i32_e32 v31, v30, v29
	v_min_i32_e32 v29, v30, v29
	v_max_i32_e32 v30, v32, v35
	v_min_i32_e32 v32, v32, v35
	v_max_i32_e32 v35, v33, v34
	v_min_i32_e32 v33, v33, v34
	v_max_i32_e32 v34, v39, v36
	v_min_i32_e32 v36, v39, v36
	v_max_i32_e32 v39, v38, v37
	v_min_i32_e32 v37, v38, v37
	v_max_i32_e32 v70, v51, v57
	v_min_i32_e32 v51, v51, v57
	v_max_i32_e32 v57, v55, v56
	v_min_i32_e32 v55, v55, v56
	v_max_i32_e32 v56, v61, v58
	v_min_i32_e32 v58, v61, v58
	v_max_i32_e32 v61, v60, v59
	v_min_i32_e32 v59, v60, v59
	v_max_i32_e32 v60, v62, v65
	v_min_i32_e32 v62, v62, v65
	v_max_i32_e32 v65, v63, v64
	v_min_i32_e32 v63, v63, v64
	v_max_i32_e32 v64, v69, v66
	v_min_i32_e32 v66, v69, v66
	v_max_i32_e32 v69, v68, v67
	v_min_i32_e32 v67, v68, v67
	v_max_i32_e32 v23, v78, v18
	v_min_i32_e32 v18, v78, v18
	v_max_i32_e32 v78, v16, v17
	v_min_i32_e32 v16, v16, v17
	v_max_i32_e32 v17, v79, v19
	v_min_i32_e32 v19, v79, v19
	v_max_i32_e32 v79, v21, v20
	v_min_i32_e32 v20, v21, v20
	v_max_i32_e32 v21, v80, v44
	v_min_i32_e32 v44, v80, v44
	v_max_i32_e32 v80, v52, v53
	v_min_i32_e32 v52, v52, v53
	v_max_i32_e32 v53, v22, v54
	v_min_i32_e32 v22, v22, v54
	v_max_i32_e32 v54, v41, v40
	v_min_i32_e32 v40, v41, v40
	v_max_i32_e32 v15, v88, v2
	v_min_i32_e32 v2, v88, v2
	v_max_i32_e32 v88, v0, v1
	v_min_i32_e32 v0, v0, v1
	v_max_i32_e32 v1, v6, v3
	v_min_i32_e32 v3, v6, v3
	v_max_i32_e32 v6, v5, v4
	v_min_i32_e32 v4, v5, v4
	v_max_i32_e32 v5, v7, v10
	v_min_i32_e32 v7, v7, v10
	v_max_i32_e32 v10, v8, v9
	v_min_i32_e32 v8, v8, v9
	v_max_i32_e32 v9, v14, v11
	v_min_i32_e32 v11, v14, v11
	v_max_i32_e32 v14, v13, v12
	v_min_i32_e32 v12, v13, v12
	v_max_i32_e32 v38, v42, v27
	v_min_i32_e32 v27, v42, v27
	v_max_i32_e32 v42, v24, v25
	v_min_i32_e32 v24, v24, v25
	v_max_i32_e32 v25, v29, v28
	v_min_i32_e32 v28, v29, v28
	v_max_i32_e32 v29, v31, v26
	v_min_i32_e32 v26, v31, v26
	v_max_i32_e32 v31, v30, v35
	v_min_i32_e32 v30, v30, v35
	v_max_i32_e32 v35, v32, v33
	v_min_i32_e32 v32, v32, v33
	v_max_i32_e32 v33, v37, v36
	v_min_i32_e32 v36, v37, v36
	v_max_i32_e32 v37, v39, v34
	v_min_i32_e32 v34, v39, v34
	v_max_i32_e32 v68, v70, v57
	v_min_i32_e32 v57, v70, v57
	v_max_i32_e32 v70, v51, v55
	v_min_i32_e32 v51, v51, v55
	v_max_i32_e32 v55, v59, v58
	v_min_i32_e32 v58, v59, v58
	v_max_i32_e32 v59, v61, v56
	v_min_i32_e32 v56, v61, v56
	v_max_i32_e32 v61, v60, v65
	v_min_i32_e32 v60, v60, v65
	v_max_i32_e32 v65, v62, v63
	v_min_i32_e32 v62, v62, v63
	v_max_i32_e32 v63, v67, v66
	v_min_i32_e32 v66, v67, v66
	v_max_i32_e32 v67, v69, v64
	v_min_i32_e32 v64, v69, v64
	v_max_i32_e32 v41, v23, v78
	v_min_i32_e32 v23, v23, v78
	v_max_i32_e32 v78, v18, v16
	v_min_i32_e32 v16, v18, v16
	v_max_i32_e32 v18, v20, v19
	v_min_i32_e32 v19, v20, v19
	v_max_i32_e32 v20, v79, v17
	v_min_i32_e32 v17, v79, v17
	v_max_i32_e32 v79, v21, v80
	v_min_i32_e32 v21, v21, v80
	v_max_i32_e32 v80, v44, v52
	v_min_i32_e32 v44, v44, v52
	v_max_i32_e32 v52, v40, v22
	v_min_i32_e32 v22, v40, v22
	v_max_i32_e32 v40, v54, v53
	v_min_i32_e32 v53, v54, v53
	v_max_i32_e32 v13, v15, v88
	v_min_i32_e32 v15, v15, v88
	v_max_i32_e32 v88, v2, v0
	v_min_i32_e32 v0, v2, v0
	v_max_i32_e32 v2, v4, v3
	v_min_i32_e32 v3, v4, v3
	v_max_i32_e32 v4, v6, v1
	v_min_i32_e32 v1, v6, v1
	v_max_i32_e32 v6, v5, v10
	v_min_i32_e32 v5, v5, v10
	v_max_i32_e32 v10, v7, v8
	v_min_i32_e32 v7, v7, v8
	v_max_i32_e32 v8, v12, v11
	v_min_i32_e32 v11, v12, v11
	v_max_i32_e32 v12, v14, v9
	v_min_i32_e32 v9, v14, v9
	v_max_i32_e32 v39, v38, v28
	v_min_i32_e32 v28, v38, v28
	v_max_i32_e32 v38, v27, v25
	v_min_i32_e32 v25, v27, v25
	v_max_i32_e32 v27, v42, v26
	v_min_i32_e32 v26, v42, v26
	v_max_i32_e32 v42, v24, v29
	v_min_i32_e32 v24, v24, v29
	v_max_i32_e32 v29, v36, v31
	v_min_i32_e32 v31, v36, v31
	v_max_i32_e32 v36, v33, v30
	v_min_i32_e32 v30, v33, v30
	v_max_i32_e32 v33, v34, v35
	v_min_i32_e32 v34, v34, v35
	v_max_i32_e32 v35, v37, v32
	v_min_i32_e32 v32, v37, v32
	v_max_i32_e32 v69, v68, v58
	v_min_i32_e32 v58, v68, v58
	v_max_i32_e32 v68, v57, v55
	v_min_i32_e32 v55, v57, v55
	v_max_i32_e32 v57, v70, v56
	v_min_i32_e32 v56, v70, v56
	v_max_i32_e32 v70, v51, v59
	v_min_i32_e32 v51, v51, v59
	v_max_i32_e32 v59, v66, v61
	v_min_i32_e32 v61, v66, v61
	v_max_i32_e32 v66, v63, v60
	v_min_i32_e32 v60, v63, v60
	v_max_i32_e32 v63, v64, v65
	v_min_i32_e32 v64, v64, v65
	v_max_i32_e32 v65, v67, v62
	v_min_i32_e32 v62, v67, v62
	v_max_i32_e32 v54, v41, v19
	v_min_i32_e32 v19, v41, v19
	v_max_i32_e32 v41, v23, v18
	v_min_i32_e32 v18, v23, v18
	v_max_i32_e32 v23, v78, v17
	v_min_i32_e32 v17, v78, v17
	v_max_i32_e32 v78, v16, v20
	v_min_i32_e32 v16, v16, v20
	v_max_i32_e32 v20, v22, v79
	v_min_i32_e32 v22, v22, v79
	v_max_i32_e32 v79, v52, v21
	v_min_i32_e32 v21, v52, v21
	v_max_i32_e32 v52, v53, v80
	v_min_i32_e32 v53, v53, v80
	v_max_i32_e32 v80, v40, v44
	v_min_i32_e32 v40, v40, v44
	v_max_i32_e32 v14, v13, v3
	v_min_i32_e32 v3, v13, v3
	v_max_i32_e32 v13, v15, v2
	v_min_i32_e32 v2, v15, v2
	v_max_i32_e32 v15, v88, v1
	v_min_i32_e32 v1, v88, v1
	v_max_i32_e32 v88, v0, v4
	v_min_i32_e32 v0, v0, v4
	v_max_i32_e32 v4, v11, v6
	v_min_i32_e32 v6, v11, v6
	v_max_i32_e32 v11, v8, v5
	v_min_i32_e32 v5, v8, v5
	v_max_i32_e32 v8, v9, v10
	v_min_i32_e32 v9, v9, v10
	v_max_i32_e32 v10, v12, v7
	v_min_i32_e32 v7, v12, v7
	v_max_i32_e32 v37, v39, v27
	v_min_i32_e32 v27, v39, v27
	v_max_i32_e32 v39, v38, v42
	v_min_i32_e32 v38, v38, v42
	v_max_i32_e32 v42, v28, v26
	v_min_i32_e32 v26, v28, v26
	v_max_i32_e32 v28, v25, v24
	v_min_i32_e32 v24, v25, v24
	v_max_i32_e32 v25, v34, v31
	v_min_i32_e32 v31, v34, v31
	v_max_i32_e32 v34, v32, v30
	v_min_i32_e32 v30, v32, v30
	v_max_i32_e32 v32, v33, v29
	v_min_i32_e32 v29, v33, v29
	v_max_i32_e32 v33, v35, v36
	v_min_i32_e32 v35, v35, v36
	v_max_i32_e32 v67, v69, v57
	v_min_i32_e32 v57, v69, v57
	v_max_i32_e32 v69, v68, v70
	v_min_i32_e32 v68, v68, v70
	v_max_i32_e32 v70, v58, v56
	v_min_i32_e32 v56, v58, v56
	v_max_i32_e32 v58, v55, v51
	v_min_i32_e32 v51, v55, v51
	v_max_i32_e32 v55, v64, v61
	v_min_i32_e32 v61, v64, v61
	v_max_i32_e32 v64, v62, v60
	v_min_i32_e32 v60, v62, v60
	v_max_i32_e32 v62, v63, v59
	v_min_i32_e32 v59, v63, v59
	v_max_i32_e32 v63, v65, v66
	v_min_i32_e32 v65, v65, v66
	v_max_i32_e32 v44, v54, v23
	v_min_i32_e32 v23, v54, v23
	v_max_i32_e32 v54, v41, v78
	v_min_i32_e32 v41, v41, v78
	v_max_i32_e32 v78, v19, v17
	v_min_i32_e32 v17, v19, v17
	v_max_i32_e32 v19, v18, v16
	v_min_i32_e32 v16, v18, v16
	v_max_i32_e32 v18, v53, v22
	v_min_i32_e32 v22, v53, v22
	v_max_i32_e32 v53, v40, v21
	v_min_i32_e32 v21, v40, v21
	v_max_i32_e32 v40, v52, v20
	v_min_i32_e32 v20, v52, v20
	v_max_i32_e32 v52, v80, v79
	v_min_i32_e32 v79, v80, v79
	v_max_i32_e32 v12, v14, v15
	v_min_i32_e32 v14, v14, v15
	v_max_i32_e32 v15, v13, v88
	v_min_i32_e32 v13, v13, v88
	v_max_i32_e32 v88, v3, v1
	v_min_i32_e32 v1, v3, v1
	v_max_i32_e32 v3, v2, v0
	v_min_i32_e32 v0, v2, v0
	v_max_i32_e32 v2, v9, v6
	v_min_i32_e32 v6, v9, v6
	v_max_i32_e32 v9, v7, v5
	v_min_i32_e32 v5, v7, v5
	v_max_i32_e32 v7, v8, v4
	v_min_i32_e32 v4, v8, v4
	v_max_i32_e32 v8, v10, v11
	v_min_i32_e32 v10, v10, v11
	v_max_i32_e32 v36, v37, v39
	v_min_i32_e32 v37, v37, v39
	v_max_i32_e32 v39, v27, v38
	v_min_i32_e32 v27, v27, v38
	v_max_i32_e32 v38, v42, v28
	v_min_i32_e32 v28, v42, v28
	v_max_i32_e32 v42, v26, v24
	v_min_i32_e32 v24, v26, v24
	v_max_i32_e32 v26, v30, v31
	v_min_i32_e32 v30, v30, v31
	v_max_i32_e32 v31, v34, v25
	v_min_i32_e32 v25, v34, v25
	v_max_i32_e32 v34, v35, v29
	v_min_i32_e32 v29, v35, v29
	v_max_i32_e32 v35, v33, v32
	v_min_i32_e32 v32, v33, v32
	v_max_i32_e32 v66, v67, v69
	v_min_i32_e32 v67, v67, v69
	v_max_i32_e32 v69, v57, v68
	v_min_i32_e32 v57, v57, v68
	v_max_i32_e32 v68, v70, v58
	v_min_i32_e32 v58, v70, v58
	v_max_i32_e32 v70, v56, v51
	v_min_i32_e32 v51, v56, v51
	v_max_i32_e32 v56, v60, v61
	v_min_i32_e32 v60, v60, v61
	v_max_i32_e32 v61, v64, v55
	v_min_i32_e32 v55, v64, v55
	v_max_i32_e32 v64, v65, v59
	v_min_i32_e32 v59, v65, v59
	v_max_i32_e32 v65, v63, v62
	v_min_i32_e32 v62, v63, v62
	v_max_i32_e32 v80, v44, v54
	v_min_i32_e32 v44, v44, v54
	v_max_i32_e32 v54, v23, v41
	v_min_i32_e32 v23, v23, v41
	v_max_i32_e32 v41, v78, v19
	v_min_i32_e32 v19, v78, v19
	v_max_i32_e32 v78, v17, v16
	v_min_i32_e32 v16, v17, v16
	v_max_i32_e32 v17, v21, v22
	v_min_i32_e32 v21, v21, v22
	v_max_i32_e32 v22, v53, v18
	v_min_i32_e32 v18, v53, v18
	v_max_i32_e32 v53, v79, v20
	v_min_i32_e32 v20, v79, v20
	v_max_i32_e32 v79, v52, v40
	v_min_i32_e32 v40, v52, v40
	v_max_i32_e32 v11, v12, v15
	v_min_i32_e32 v12, v12, v15
	v_max_i32_e32 v15, v14, v13
	v_min_i32_e32 v13, v14, v13
	v_max_i32_e32 v14, v88, v3
	v_min_i32_e32 v3, v88, v3
	v_max_i32_e32 v88, v1, v0
	v_min_i32_e32 v0, v1, v0
	v_max_i32_e32 v1, v5, v6
	v_min_i32_e32 v5, v5, v6
	v_max_i32_e32 v6, v9, v2
	v_min_i32_e32 v2, v9, v2
	v_max_i32_e32 v9, v10, v4
	v_min_i32_e32 v4, v10, v4
	v_max_i32_e32 v10, v8, v7
	v_min_i32_e32 v7, v8, v7
	v_max_i32_e32 v33, v36, v30
	v_min_i32_e32 v30, v36, v30
	v_max_i32_e32 v36, v37, v26
	v_min_i32_e32 v26, v37, v26
	v_max_i32_e32 v37, v39, v25
	v_min_i32_e32 v25, v39, v25
	v_max_i32_e32 v39, v27, v31
	v_min_i32_e32 v27, v27, v31
	v_max_i32_e32 v31, v38, v29
	v_min_i32_e32 v29, v38, v29
	v_max_i32_e32 v38, v28, v34
	v_min_i32_e32 v28, v28, v34
	v_max_i32_e32 v34, v42, v32
	v_min_i32_e32 v32, v42, v32
	v_max_i32_e32 v42, v24, v35
	v_min_i32_e32 v24, v24, v35
	v_max_i32_e32 v63, v66, v60
	v_min_i32_e32 v60, v66, v60
	v_max_i32_e32 v66, v67, v56
	v_min_i32_e32 v56, v67, v56
	v_max_i32_e32 v67, v69, v55
	v_min_i32_e32 v55, v69, v55
	v_max_i32_e32 v69, v57, v61
	v_min_i32_e32 v57, v57, v61
	v_max_i32_e32 v61, v68, v59
	v_min_i32_e32 v59, v68, v59
	v_max_i32_e32 v68, v58, v64
	v_min_i32_e32 v58, v58, v64
	v_max_i32_e32 v64, v70, v62
	v_min_i32_e32 v62, v70, v62
	v_max_i32_e32 v70, v51, v65
	v_min_i32_e32 v51, v51, v65
	v_max_i32_e32 v52, v80, v21
	v_min_i32_e32 v21, v80, v21
	v_max_i32_e32 v80, v44, v17
	v_min_i32_e32 v17, v44, v17
	v_max_i32_e32 v44, v54, v18
	v_min_i32_e32 v18, v54, v18
	v_max_i32_e32 v54, v23, v22
	v_min_i32_e32 v22, v23, v22
	v_max_i32_e32 v23, v41, v20
	v_min_i32_e32 v20, v41, v20
	v_max_i32_e32 v41, v19, v53
	v_min_i32_e32 v19, v19, v53
	v_max_i32_e32 v53, v78, v40
	v_min_i32_e32 v40, v78, v40
	v_max_i32_e32 v78, v16, v79
	v_min_i32_e32 v16, v16, v79
	v_max_i32_e32 v8, v11, v5
	v_min_i32_e32 v5, v11, v5
	v_max_i32_e32 v11, v12, v1
	v_min_i32_e32 v1, v12, v1
	v_max_i32_e32 v12, v15, v2
	v_min_i32_e32 v2, v15, v2
	v_max_i32_e32 v15, v13, v6
	v_min_i32_e32 v6, v13, v6
	v_max_i32_e32 v13, v14, v4
	v_min_i32_e32 v4, v14, v4
	v_max_i32_e32 v14, v3, v9
	v_min_i32_e32 v3, v3, v9
	v_max_i32_e32 v9, v88, v7
	v_min_i32_e32 v7, v88, v7
	v_max_i32_e32 v88, v0, v10
	v_min_i32_e32 v0, v0, v10
	v_max_i32_e32 v35, v33, v31
	v_min_i32_e32 v31, v33, v31
	v_max_i32_e32 v33, v36, v38
	v_min_i32_e32 v36, v36, v38
	v_max_i32_e32 v38, v37, v34
	v_min_i32_e32 v34, v37, v34
	v_max_i32_e32 v37, v39, v42
	v_min_i32_e32 v39, v39, v42
	v_max_i32_e32 v42, v30, v29
	v_min_i32_e32 v29, v30, v29
	v_max_i32_e32 v30, v26, v28
	v_min_i32_e32 v26, v26, v28
	v_max_i32_e32 v28, v25, v32
	v_min_i32_e32 v25, v25, v32
	v_max_i32_e32 v32, v27, v24
	v_min_i32_e32 v24, v27, v24
	v_max_i32_e32 v65, v63, v61
	v_min_i32_e32 v61, v63, v61
	v_max_i32_e32 v63, v66, v68
	v_min_i32_e32 v66, v66, v68
	v_max_i32_e32 v68, v67, v64
	v_min_i32_e32 v64, v67, v64
	v_max_i32_e32 v67, v69, v70
	v_min_i32_e32 v69, v69, v70
	v_max_i32_e32 v70, v60, v59
	v_min_i32_e32 v59, v60, v59
	v_max_i32_e32 v60, v56, v58
	v_min_i32_e32 v56, v56, v58
	v_max_i32_e32 v58, v55, v62
	v_min_i32_e32 v55, v55, v62
	v_max_i32_e32 v62, v57, v51
	v_min_i32_e32 v51, v57, v51
	v_max_i32_e32 v79, v52, v23
	v_min_i32_e32 v23, v52, v23
	v_max_i32_e32 v52, v80, v41
	v_min_i32_e32 v41, v80, v41
	v_max_i32_e32 v80, v44, v53
	v_min_i32_e32 v44, v44, v53
	v_max_i32_e32 v53, v54, v78
	v_min_i32_e32 v54, v54, v78
	v_max_i32_e32 v78, v21, v20
	v_min_i32_e32 v20, v21, v20
	v_max_i32_e32 v21, v17, v19
	v_min_i32_e32 v17, v17, v19
	v_max_i32_e32 v19, v18, v40
	v_min_i32_e32 v18, v18, v40
	v_max_i32_e32 v40, v22, v16
	v_min_i32_e32 v16, v22, v16
	v_max_i32_e32 v10, v8, v13
	v_min_i32_e32 v8, v8, v13
	v_max_i32_e32 v13, v11, v14
	v_min_i32_e32 v11, v11, v14
	v_max_i32_e32 v14, v12, v9
	v_min_i32_e32 v9, v12, v9
	v_max_i32_e32 v12, v15, v88
	v_min_i32_e32 v15, v15, v88
	v_max_i32_e32 v88, v5, v4
	v_min_i32_e32 v4, v5, v4
	v_max_i32_e32 v5, v1, v3
	v_min_i32_e32 v1, v1, v3
	v_max_i32_e32 v3, v2, v7
	v_min_i32_e32 v2, v2, v7
	v_max_i32_e32 v7, v6, v0
	v_min_i32_e32 v0, v6, v0
	v_max_i32_e32 v27, v35, v38
	v_min_i32_e32 v35, v35, v38
	v_max_i32_e32 v38, v33, v37
	v_min_i32_e32 v33, v33, v37
	v_max_i32_e32 v37, v31, v34
	v_min_i32_e32 v31, v31, v34
	v_max_i32_e32 v34, v36, v39
	v_min_i32_e32 v36, v36, v39
	v_max_i32_e32 v39, v42, v28
	v_min_i32_e32 v28, v42, v28
	v_max_i32_e32 v42, v30, v32
	v_min_i32_e32 v30, v30, v32
	v_max_i32_e32 v32, v29, v25
	v_min_i32_e32 v25, v29, v25
	v_max_i32_e32 v29, v26, v24
	v_min_i32_e32 v24, v26, v24
	v_max_i32_e32 v57, v65, v68
	v_min_i32_e32 v65, v65, v68
	v_max_i32_e32 v68, v63, v67
	v_min_i32_e32 v63, v63, v67
	v_max_i32_e32 v67, v61, v64
	v_min_i32_e32 v61, v61, v64
	v_max_i32_e32 v64, v66, v69
	v_min_i32_e32 v66, v66, v69
	v_max_i32_e32 v69, v70, v58
	v_min_i32_e32 v58, v70, v58
	v_max_i32_e32 v70, v60, v62
	v_min_i32_e32 v60, v60, v62
	v_max_i32_e32 v62, v59, v55
	v_min_i32_e32 v55, v59, v55
	v_max_i32_e32 v59, v56, v51
	v_min_i32_e32 v51, v56, v51
	v_max_i32_e32 v22, v79, v80
	v_min_i32_e32 v79, v79, v80
	v_max_i32_e32 v80, v52, v53
	v_min_i32_e32 v52, v52, v53
	v_max_i32_e32 v53, v23, v44
	v_min_i32_e32 v23, v23, v44
	v_max_i32_e32 v44, v41, v54
	v_min_i32_e32 v41, v41, v54
	v_max_i32_e32 v54, v78, v19
	v_min_i32_e32 v19, v78, v19
	v_max_i32_e32 v78, v21, v40
	v_min_i32_e32 v21, v21, v40
	v_max_i32_e32 v40, v20, v18
	v_min_i32_e32 v18, v20, v18
	v_max_i32_e32 v20, v17, v16
	v_min_i32_e32 v16, v17, v16
	v_max_i32_e32 v6, v10, v14
	v_min_i32_e32 v10, v10, v14
	v_max_i32_e32 v14, v13, v12
	v_min_i32_e32 v12, v13, v12
	v_max_i32_e32 v13, v8, v9
	v_min_i32_e32 v8, v8, v9
	v_max_i32_e32 v9, v11, v15
	v_min_i32_e32 v11, v11, v15
	v_max_i32_e32 v15, v88, v3
	v_min_i32_e32 v3, v88, v3
	v_max_i32_e32 v88, v5, v7
	v_min_i32_e32 v5, v5, v7
	v_max_i32_e32 v7, v4, v2
	v_min_i32_e32 v2, v4, v2
	v_max_i32_e32 v4, v1, v0
	v_min_i32_e32 v0, v1, v0
	v_min_i32_e32 v26, v27, v38
	v_min_i32_e32 v43, v35, v33
	v_min_i32_e32 v45, v37, v34
	v_min_i32_e32 v46, v31, v36
	v_min_i32_e32 v47, v39, v42
	v_min_i32_e32 v48, v28, v30
	v_min_i32_e32 v49, v32, v29
	v_min_i32_e32 v50, v25, v24
	v_min_i32_e32 v56, v57, v68
	v_min_i32_e32 v71, v65, v63
	v_min_i32_e32 v72, v67, v64
	v_min_i32_e32 v73, v61, v66
	v_min_i32_e32 v74, v69, v70
	v_min_i32_e32 v75, v58, v60
	v_min_i32_e32 v76, v62, v59
	v_min_i32_e32 v77, v55, v51
	v_min_i32_e32 v17, v22, v80
	v_min_i32_e32 v81, v79, v52
	v_min_i32_e32 v82, v53, v44
	v_min_i32_e32 v83, v23, v41
	v_min_i32_e32 v84, v54, v78
	v_min_i32_e32 v85, v19, v21
	v_min_i32_e32 v86, v40, v20
	v_min_i32_e32 v87, v18, v16
	v_min_i32_e32 v1, v6, v14
	v_min_i32_e32 v89, v10, v12
	v_min_i32_e32 v90, v13, v9
	v_min_i32_e32 v91, v8, v11
	v_min_i32_e32 v92, v15, v88
	v_min_i32_e32 v93, v3, v5
	v_min_i32_e32 v94, v7, v4
	v_min_i32_e32 v95, v2, v0
	v_max3_i32 v27, v27, v38, v77
	v_max3_i32 v26, v26, v55, v51
	v_max3_i32 v33, v35, v33, v76
	v_max3_i32 v35, v43, v62, v59
	v_max3_i32 v34, v37, v34, v75
	v_max3_i32 v37, v45, v58, v60
	v_max3_i32 v31, v31, v36, v74
	v_max3_i32 v36, v46, v69, v70
	v_max3_i32 v38, v39, v42, v73
	v_max3_i32 v39, v47, v61, v66
	v_max3_i32 v28, v28, v30, v72
	v_max3_i32 v30, v48, v67, v64
	v_max3_i32 v29, v32, v29, v71
	v_max3_i32 v32, v49, v65, v63
	v_max3_i32 v24, v25, v24, v56
	v_max3_i32 v25, v50, v57, v68
	v_max3_i32 v22, v22, v80, v95
	v_max3_i32 v0, v17, v2, v0
	v_max3_i32 v2, v79, v52, v94
	v_max3_i32 v4, v81, v7, v4
	v_max3_i32 v7, v53, v44, v93
	v_max3_i32 v3, v82, v3, v5
	v_max3_i32 v5, v23, v41, v92
	v_max3_i32 v15, v83, v15, v88
	v_max3_i32 v17, v54, v78, v91
	v_max3_i32 v8, v84, v8, v11
	v_max3_i32 v11, v19, v21, v90
	v_max3_i32 v9, v85, v13, v9
	v_max3_i32 v13, v40, v20, v89
	v_max3_i32 v10, v86, v10, v12
	v_max3_i32 v1, v18, v16, v1
	v_max3_i32 v6, v87, v6, v14
	v_max_i32_e32 v42, v27, v38
	v_min_i32_e32 v27, v27, v38
	v_max_i32_e32 v38, v26, v39
	v_min_i32_e32 v26, v26, v39
	v_max_i32_e32 v39, v33, v28
	v_min_i32_e32 v28, v33, v28
	v_max_i32_e32 v33, v35, v30
	v_min_i32_e32 v30, v35, v30
	v_max_i32_e32 v35, v34, v29
	v_min_i32_e32 v29, v34, v29
	v_max_i32_e32 v34, v37, v32
	v_min_i32_e32 v32, v37, v32
	v_max_i32_e32 v37, v31, v24
	v_min_i32_e32 v24, v31, v24
	v_max_i32_e32 v31, v36, v25
	v_min_i32_e32 v25, v36, v25
	v_max_i32_e32 v12, v22, v17
	v_min_i32_e32 v14, v22, v17
	v_max_i32_e32 v16, v0, v8
	v_min_i32_e32 v0, v0, v8
	v_max_i32_e32 v8, v2, v11
	v_min_i32_e32 v2, v2, v11
	v_max_i32_e32 v11, v4, v9
	v_min_i32_e32 v4, v4, v9
	v_max_i32_e32 v9, v7, v13
	v_min_i32_e32 v7, v7, v13
	v_max_i32_e32 v13, v3, v10
	v_min_i32_e32 v3, v3, v10
	v_max_i32_e32 v10, v5, v1
	v_min_i32_e32 v1, v5, v1
	v_max_i32_e32 v5, v15, v6
	v_min_i32_e32 v6, v15, v6
	v_max_i32_e32 v36, v42, v35
	v_min_i32_e32 v35, v42, v35
	v_max_i32_e32 v42, v38, v34
	v_min_i32_e32 v34, v38, v34
	v_max_i32_e32 v38, v39, v37
	v_min_i32_e32 v37, v39, v37
	v_max_i32_e32 v39, v33, v31
	v_min_i32_e32 v31, v33, v31
	v_max_i32_e32 v33, v27, v29
	v_min_i32_e32 v27, v27, v29
	v_max_i32_e32 v29, v26, v32
	v_min_i32_e32 v26, v26, v32
	v_max_i32_e32 v32, v28, v24
	v_min_i32_e32 v24, v28, v24
	v_max_i32_e32 v28, v30, v25
	v_min_i32_e32 v25, v30, v25
	v_max_i32_e32 v15, v12, v9
	v_min_i32_e32 v9, v12, v9
	v_max_i32_e32 v12, v16, v13
	v_min_i32_e32 v13, v16, v13
	v_max_i32_e32 v16, v8, v10
	v_min_i32_e32 v8, v8, v10
	v_max_i32_e32 v10, v11, v5
	v_min_i32_e32 v5, v11, v5
	v_max_i32_e32 v11, v14, v7
	v_min_i32_e32 v7, v14, v7
	v_max_i32_e32 v14, v0, v3
	v_min_i32_e32 v0, v0, v3
	v_max_i32_e32 v3, v2, v1
	v_min_i32_e32 v1, v2, v1
	v_max_i32_e32 v2, v4, v6
	v_min_i32_e32 v4, v4, v6
	v_max_i32_e32 v30, v36, v38
	v_min_i32_e32 v36, v36, v38
	v_max_i32_e32 v38, v42, v39
	v_min_i32_e32 v39, v42, v39
	v_max_i32_e32 v42, v35, v37
	v_min_i32_e32 v35, v35, v37
	v_max_i32_e32 v37, v34, v31
	v_min_i32_e32 v31, v34, v31
	v_max_i32_e32 v34, v33, v32
	v_min_i32_e32 v32, v33, v32
	v_max_i32_e32 v33, v29, v28
	v_min_i32_e32 v28, v29, v28
	v_max_i32_e32 v29, v27, v24
	v_min_i32_e32 v24, v27, v24
	v_max_i32_e32 v27, v26, v25
	v_min_i32_e32 v25, v26, v25
	v_max_i32_e32 v6, v15, v16
	v_min_i32_e32 v15, v15, v16
	v_max_i32_e32 v16, v12, v10
	v_min_i32_e32 v10, v12, v10
	v_max_i32_e32 v12, v9, v8
	v_min_i32_e32 v8, v9, v8
	v_max_i32_e32 v9, v13, v5
	v_min_i32_e32 v5, v13, v5
	v_max_i32_e32 v13, v11, v3
	v_min_i32_e32 v3, v11, v3
	v_max_i32_e32 v11, v14, v2
	v_min_i32_e32 v2, v14, v2
	v_max_i32_e32 v14, v7, v1
	v_min_i32_e32 v1, v7, v1
	v_max_i32_e32 v7, v0, v4
	v_min_i32_e32 v0, v0, v4
	v_min_i32_e32 v26, v30, v38
	v_min_i32_e32 v43, v36, v39
	v_min_i32_e32 v45, v42, v37
	v_min_i32_e32 v46, v35, v31
	v_min_i32_e32 v47, v34, v33
	v_min_i32_e32 v48, v32, v28
	v_min_i32_e32 v49, v29, v27
	v_min_i32_e32 v50, v24, v25
	v_min_i32_e32 v4, v6, v16
	v_min_i32_e32 v17, v15, v10
	v_min_i32_e32 v18, v12, v9
	v_min_i32_e32 v19, v8, v5
	v_min_i32_e32 v20, v13, v11
	v_min_i32_e32 v21, v3, v2
	v_min_i32_e32 v22, v14, v7
	v_min_i32_e32 v23, v1, v0
	v_max3_i32 v23, v30, v38, v23
	v_max3_i32 v0, v26, v1, v0
	v_max3_i32 v1, v36, v39, v22
	v_max3_i32 v7, v43, v14, v7
	v_max3_i32 v14, v42, v37, v21
	v_max3_i32 v2, v45, v3, v2
	v_max3_i32 v3, v35, v31, v20
	v_max3_i32 v11, v46, v13, v11
	v_max3_i32 v13, v34, v33, v19
	v_max3_i32 v5, v47, v8, v5
	v_max3_i32 v8, v32, v28, v18
	v_max3_i32 v9, v48, v12, v9
	v_max3_i32 v12, v29, v27, v17
	v_max3_i32 v10, v49, v15, v10
	v_max3_i32 v4, v24, v25, v4
	v_max3_i32 v6, v50, v6, v16
	v_max_i32_e32 v15, v23, v13
	v_min_i32_e32 v13, v23, v13
	v_max_i32_e32 v16, v0, v5
	v_min_i32_e32 v0, v0, v5
	v_max_i32_e32 v5, v1, v8
	v_min_i32_e32 v1, v1, v8
	v_max_i32_e32 v8, v7, v9
	v_min_i32_e32 v7, v7, v9
	v_max_i32_e32 v9, v14, v12
	v_min_i32_e32 v12, v14, v12
	v_max_i32_e32 v14, v2, v10
	v_min_i32_e32 v2, v2, v10
	v_max_i32_e32 v10, v3, v4
	v_min_i32_e32 v3, v3, v4
	v_max_i32_e32 v4, v11, v6
	v_min_i32_e32 v6, v11, v6
	v_max_i32_e32 v11, v15, v9
	v_min_i32_e32 v9, v15, v9
	v_max_i32_e32 v15, v16, v14
	v_min_i32_e32 v14, v16, v14
	v_max_i32_e32 v16, v5, v10
	v_min_i32_e32 v5, v5, v10
	v_max_i32_e32 v10, v8, v4
	v_min_i32_e32 v4, v8, v4
	v_max_i32_e32 v8, v13, v12
	v_min_i32_e32 v12, v13, v12
	v_max_i32_e32 v13, v0, v2
	v_min_i32_e32 v0, v0, v2
	v_max_i32_e32 v2, v1, v3
	v_min_i32_e32 v1, v1, v3
	v_max_i32_e32 v3, v7, v6
	v_min_i32_e32 v6, v7, v6
	v_max_i32_e32 v7, v11, v16
	v_min_i32_e32 v11, v11, v16
	v_max_i32_e32 v16, v15, v10
	v_min_i32_e32 v10, v15, v10
	v_max_i32_e32 v15, v9, v5
	v_min_i32_e32 v5, v9, v5
	v_max_i32_e32 v9, v14, v4
	v_min_i32_e32 v4, v14, v4
	v_max_i32_e32 v14, v8, v2
	v_min_i32_e32 v2, v8, v2
	v_max_i32_e32 v8, v13, v3
	v_min_i32_e32 v3, v13, v3
	v_max_i32_e32 v13, v12, v1
	v_min_i32_e32 v1, v12, v1
	v_max_i32_e32 v12, v0, v6
	v_min_i32_e32 v0, v0, v6
	v_max_i32_e32 v6, v7, v16
	v_min_i32_e32 v7, v7, v16
	v_max_i32_e32 v16, v11, v10
	v_min_i32_e32 v10, v11, v10
	v_max_i32_e32 v11, v15, v9
	v_min_i32_e32 v9, v15, v9
	v_max_i32_e32 v15, v5, v4
	v_min_i32_e32 v4, v5, v4
	v_max_i32_e32 v5, v14, v8
	v_min_i32_e32 v8, v14, v8
	v_max_i32_e32 v14, v2, v3
	v_min_i32_e32 v2, v2, v3
	v_max_i32_e32 v3, v13, v12
	v_min_i32_e32 v13, v13, v12
	v_and_b32_e32 v12, 64, v188
	v_max_i32_e32 v17, v1, v0
	v_min_i32_e32 v0, v1, v0
	v_xor_b32_e32 v1, 32, v188
	v_add_u32_e32 v12, 64, v12
	v_cmp_lt_i32_e32 vcc, v1, v12
	s_barrier
	s_nop 0
	v_cndmask_b32_e32 v1, v188, v1, vcc
	v_lshlrev_b32_e32 v12, 2, v1
	ds_bpermute_b32 v1, v12, v6
	ds_bpermute_b32 v18, v12, v7
	ds_bpermute_b32 v19, v12, v16
	ds_bpermute_b32 v20, v12, v10
	ds_bpermute_b32 v21, v12, v11
	ds_bpermute_b32 v22, v12, v9
	ds_bpermute_b32 v23, v12, v15
	ds_bpermute_b32 v24, v12, v4
	ds_bpermute_b32 v25, v12, v5
	ds_bpermute_b32 v26, v12, v8
	ds_bpermute_b32 v27, v12, v14
	ds_bpermute_b32 v28, v12, v0
	ds_bpermute_b32 v29, v12, v17
	ds_bpermute_b32 v30, v12, v13
	ds_bpermute_b32 v31, v12, v3
	ds_bpermute_b32 v32, v12, v2
	s_waitcnt lgkmcnt(4)
	v_max_i32_e32 v6, v6, v28
	s_waitcnt lgkmcnt(3)
	v_max_i32_e32 v7, v7, v29
	s_waitcnt lgkmcnt(2)
	v_max_i32_e32 v16, v16, v30
	s_waitcnt lgkmcnt(1)
	v_max_i32_e32 v10, v10, v31
	s_waitcnt lgkmcnt(0)
	v_max_i32_e32 v11, v11, v32
	v_max_i32_e32 v9, v9, v27
	v_max_i32_e32 v15, v15, v26
	v_max_i32_e32 v4, v4, v25
	v_max_i32_e32 v5, v5, v24
	v_max_i32_e32 v8, v8, v23
	v_max_i32_e32 v14, v14, v22
	v_max_i32_e32 v2, v2, v21
	v_max_i32_e32 v3, v3, v20
	v_max_i32_e32 v13, v13, v19
	v_max_i32_e32 v17, v17, v18
	v_max_i32_e32 v0, v0, v1
	v_max_i32_e32 v1, v6, v5
	v_min_i32_e32 v5, v6, v5
	v_max_i32_e32 v6, v7, v8
	v_min_i32_e32 v7, v7, v8
	v_max_i32_e32 v8, v16, v14
	v_min_i32_e32 v14, v16, v14
	v_max_i32_e32 v16, v10, v2
	v_min_i32_e32 v2, v10, v2
	v_max_i32_e32 v10, v11, v3
	v_min_i32_e32 v3, v11, v3
	v_max_i32_e32 v11, v9, v13
	v_min_i32_e32 v9, v9, v13
	v_max_i32_e32 v13, v15, v17
	v_min_i32_e32 v15, v15, v17
	v_max_i32_e32 v17, v4, v0
	v_min_i32_e32 v0, v4, v0
	v_max_i32_e32 v4, v1, v10
	v_min_i32_e32 v1, v1, v10
	v_max_i32_e32 v10, v6, v11
	v_min_i32_e32 v6, v6, v11
	v_max_i32_e32 v11, v8, v13
	v_min_i32_e32 v8, v8, v13
	v_max_i32_e32 v13, v16, v17
	v_min_i32_e32 v16, v16, v17
	v_max_i32_e32 v17, v5, v3
	v_min_i32_e32 v3, v5, v3
	v_max_i32_e32 v5, v7, v9
	v_min_i32_e32 v7, v7, v9
	v_max_i32_e32 v9, v14, v15
	v_min_i32_e32 v14, v14, v15
	v_max_i32_e32 v15, v2, v0
	v_min_i32_e32 v0, v2, v0
	v_max_i32_e32 v2, v4, v11
	v_min_i32_e32 v4, v4, v11
	v_max_i32_e32 v11, v10, v13
	v_min_i32_e32 v10, v10, v13
	v_max_i32_e32 v13, v1, v8
	v_min_i32_e32 v1, v1, v8
	v_max_i32_e32 v8, v6, v16
	v_min_i32_e32 v6, v6, v16
	v_max_i32_e32 v16, v17, v9
	v_min_i32_e32 v9, v17, v9
	v_max_i32_e32 v17, v5, v15
	v_min_i32_e32 v5, v5, v15
	v_max_i32_e32 v15, v3, v14
	v_min_i32_e32 v3, v3, v14
	v_max_i32_e32 v14, v7, v0
	v_min_i32_e32 v0, v7, v0
	v_max_i32_e32 v7, v2, v11
	v_min_i32_e32 v2, v2, v11
	v_max_i32_e32 v25, v3, v0
	v_min_i32_e32 v26, v3, v0
	v_ashrrev_i32_e32 v0, 31, v7
	v_max_i32_e32 v11, v4, v10
	v_bitop3_b32 v20, v0, v7, s11 bitop3:0x6c
	v_ashrrev_i32_e32 v0, 31, v2
	v_min_i32_e32 v4, v4, v10
	v_bitop3_b32 v19, v0, v2, s11 bitop3:0x6c
	v_ashrrev_i32_e32 v0, 31, v11
	v_max_i32_e32 v10, v13, v8
	v_bitop3_b32 v18, v0, v11, s11 bitop3:0x6c
	v_ashrrev_i32_e32 v0, 31, v4
	v_min_i32_e32 v8, v13, v8
	v_max_i32_e32 v13, v1, v6
	v_min_i32_e32 v1, v1, v6
	v_max_i32_e32 v6, v16, v17
	v_min_i32_e32 v21, v16, v17
	v_bitop3_b32 v17, v0, v4, s11 bitop3:0x6c
	v_ashrrev_i32_e32 v0, 31, v10
	v_bitop3_b32 v16, v0, v10, s11 bitop3:0x6c
	v_ashrrev_i32_e32 v0, 31, v8
	v_max_i32_e32 v23, v15, v14
	v_min_i32_e32 v24, v15, v14
	v_bitop3_b32 v15, v0, v8, s11 bitop3:0x6c
	v_ashrrev_i32_e32 v0, 31, v13
	v_bitop3_b32 v14, v0, v13, s11 bitop3:0x6c
	v_ashrrev_i32_e32 v0, 31, v1
	v_bitop3_b32 v13, v0, v1, s11 bitop3:0x6c
	v_ashrrev_i32_e32 v0, 31, v6
	v_ashrrev_i32_e32 v1, 31, v21
	v_max_i32_e32 v22, v9, v5
	v_min_i32_e32 v9, v9, v5
	v_and_b32_e32 v0, 0x7fffffff, v0
	v_and_b32_e32 v2, 0x7fffffff, v1
	v_xor_b32_e32 v1, v0, v6
	v_xor_b32_e32 v0, v2, v21
	v_ashrrev_i32_e32 v2, 31, v22
	v_ashrrev_i32_e32 v3, 31, v9
	v_and_b32_e32 v2, 0x7fffffff, v2
	v_and_b32_e32 v3, 0x7fffffff, v3
	v_xor_b32_e32 v5, v2, v22
	v_xor_b32_e32 v4, v3, v9
	v_ashrrev_i32_e32 v2, 31, v23
	v_ashrrev_i32_e32 v3, 31, v24
	v_and_b32_e32 v2, 0x7fffffff, v2
	v_and_b32_e32 v6, 0x7fffffff, v3
	v_xor_b32_e32 v3, v2, v23
	v_xor_b32_e32 v2, v6, v24
	v_ashrrev_i32_e32 v6, 31, v25
	v_bitop3_b32 v11, v6, v25, s11 bitop3:0x6c
	v_ashrrev_i32_e32 v6, 31, v26
	v_bitop3_b32 v10, v6, v26, s11 bitop3:0x6c
	s_and_b64 vcc, exec, s[56:57]
	s_cbranch_vccnz .LBB0_1001
	v_mov_b32_e32 v221, v20
	v_mov_b32_e32 v222, v19
	v_mov_b32_e32 v223, v18
	v_mov_b32_e32 v224, v17
	v_mov_b32_e32 v225, v16
	v_mov_b32_e32 v226, v15
	v_mov_b32_e32 v227, v14
	v_mov_b32_e32 v228, v13
	v_mov_b32_e32 v229, v11
	v_mov_b32_e32 v230, v10
	v_mov_b64_e32 v[154:155], v[2:3]
	v_mov_b64_e32 v[156:157], v[4:5]
	v_mov_b64_e32 v[158:159], v[0:1]
	s_branch .LBB0_1003
